# mla_row: q-/kv-latent RMSNorm gain vectors loaded once before the row loop instead of per row
# speedup vs baseline: 1.0118x; 1.0002x over previous
; DI void unpack8(u32x4 w, float* v) { v[0] = lo16(w.x); v[1] = hi16(w.x); v[2] = lo16(w.y); v[3] = hi16(w.y); v[4] = lo16(w.z); v[5] = hi16(w.z); v[6] = lo16(w.w); v[7] = hi16(w.w); }
; DI u32x4 pack8(const float* v) { u32x4 w; w.x = pk2(v[0], v[1]); w.y = pk2(v[2], v[3]); w.z = pk2(v[4], v[5]); w.w = pk2(v[6], v[7]); return w; }
; DI float wave_sum(float v) { for (int o = 32; o >= 1; o >>= 1) v += __shfl_xor(v, o); return v; }
; DI void mla_row(CP c, int l, int r, int lane) {
;     unsigned char* ws = c->ws; const bf16_t* z = (const bf16_t*)(ws + WS_Z1) + (size_t)r * NZ1;
;     const bool samp = r >= MP; const int b = (r - MP) >> 4, t = (r - MP) & 15;
;     {
;         float v[8]; float ss = 0.f;
;         if (lane < 48) { unpack8(*(const u32x4*)(z + 3080 + lane * 8), v);
; #pragma unroll
;             for (int j = 0; j < 8; ++j) ss += v[j] * v[j]; }
;         const float rs = rsqrtf(wave_sum(ss) * (1.f / 384.f) + 1e-6f);
;         if (lane < 48) { const float* g = c->in[I_QNG] + l * 384 + lane * 8;
; #pragma unroll
;             for (int j = 0; j < 8; ++j) v[j] = v[j] * rs * g[j];
;             *(u32x4*)((bf16_t*)(ws + WS_QN) + (size_t)r * 384 + lane * 8) = pack8(v); }
;     }
;     {
;         float v[8]; float ss = 0.f;
;         if (lane < 32) { unpack8(*(const u32x4*)(z + 3464 + lane * 8), v);
; #pragma unroll
;             for (int j = 0; j < 8; ++j) ss += v[j] * v[j]; }
;         const float rs = rsqrtf(wave_sum(ss) * (1.f / 256.f) + 1e-6f);
;         if (lane < 32) { const float* g = c->in[I_KVNG] + l * 256 + lane * 8;
; #pragma unroll
;             for (int j = 0; j < 8; ++j) v[j] = v[j] * rs * g[j];
;             *(u32x4*)((bf16_t*)(ws + WS_LAT) + (size_t)r * 256 + lane * 8) = pack8(v);
;             float* o = samp ? c->out + O_SLAT + ((size_t)(l * 32 + b) * 16 + t) * 256 + lane * 8 : c->out + O_PLAT + ((size_t)l * MP + r) * 256 + lane * 8;
;             *(f32x4*)o = (f32x4){v[0], v[1], v[2], v[3]}; *(f32x4*)(o + 4) = (f32x4){v[4], v[5], v[6], v[7]};
;             if (samp) { bf16_t* lt = (bf16_t*)(ws + WS_LATT) + ((size_t)b * 256 + lane * 8) * LTS + 2048 + t;
.LBB0_1049:
	v_ashrrev_i32_e32 v0, 6, v212
	v_readlane_b32 s0, v252, 39
	v_readlane_b32 s1, v252, 40
	s_waitcnt vmcnt(0)
	v_add_u32_e32 v10, s0, v0
	s_movk_i32 s0, 0x4200
	v_cmp_gt_i32_e32 vcc, s0, v10
	s_and_saveexec_b64 s[0:1], vcc
	s_cbranch_execz .LBB0_1076
	v_and_b32_e32 v0, 64, v196
	v_add_u32_e32 v0, 64, v0
	v_xor_b32_e32 v2, 32, v196
	v_cmp_lt_i32_e32 vcc, v2, v0
	v_readlane_b32 s6, v254, 30
	v_readlane_b32 s7, v254, 31
	v_cndmask_b32_e32 v2, v196, v2, vcc
	v_lshlrev_b32_e32 v13, 2, v2
	v_xor_b32_e32 v2, 16, v196
	v_cmp_lt_i32_e32 vcc, v2, v0
	v_and_b32_e32 v12, 63, v212
	s_mul_i32 s12, s6, 0x180
	v_cndmask_b32_e32 v2, v196, v2, vcc
	v_lshlrev_b32_e32 v42, 2, v2
	v_xor_b32_e32 v2, 8, v196
	v_cmp_lt_i32_e32 vcc, v2, v0
	s_lshl_b32 s16, s6, 8
	s_lshl_b64 s[8:9], s[6:7], 24
	v_cndmask_b32_e32 v2, v196, v2, vcc
	v_lshlrev_b32_e32 v43, 2, v2
	v_xor_b32_e32 v2, 4, v196
	v_cmp_lt_i32_e32 vcc, v2, v0
	s_lshl_b64 s[18:19], s[6:7], 22
	s_mul_i32 s6, s6, 3
	v_cndmask_b32_e32 v2, v196, v2, vcc
	v_lshlrev_b32_e32 v44, 2, v2
	v_xor_b32_e32 v2, 2, v196
	v_cmp_lt_i32_e32 vcc, v2, v0
	v_lshlrev_b32_e32 v14, 3, v12
	v_mov_b32_e32 v15, v1
	v_cndmask_b32_e32 v2, v196, v2, vcc
	v_lshlrev_b32_e32 v45, 2, v2
	v_xor_b32_e32 v2, 1, v196
	v_cmp_lt_i32_e32 vcc, v2, v0
	s_ashr_i32 s13, s12, 31
	s_ashr_i32 s17, s16, 31
	v_cndmask_b32_e32 v0, v196, v2, vcc
	s_ashr_i32 s7, s6, 31
	v_lshlrev_b32_e32 v46, 2, v0
	s_waitcnt lgkmcnt(0)
	v_lshl_add_u64 v[2:3], s[20:21], 0, v[14:15]
	s_mov_b64 s[22:23], 0x384000
	v_lshlrev_b32_e32 v0, 4, v12
	v_lshl_add_u64 v[16:17], v[2:3], 0, s[22:23]
	v_mad_i64_i32 v[4:5], s[22:23], v10, s77, v[0:1]
	s_add_u32 s18, s18, 0x6200000
	v_ashrrev_i32_e32 v11, 31, v10
	s_mov_b64 s[22:23], 0x10d14000
	s_addc_u32 s19, s19, 0
	v_lshl_add_u64 v[18:19], v[4:5], 0, s[22:23]
	v_lshlrev_b64 v[4:5], 8, v[10:11]
	s_add_u32 s8, s8, 0x4200000
	v_lshl_add_u64 v[20:21], s[18:19], 0, v[4:5]
	s_addc_u32 s9, s9, 0
	v_lshlrev_b64 v[4:5], 10, v[10:11]
	v_lshlrev_b64 v[6:7], 9, v[10:11]
	v_lshl_add_u64 v[24:25], s[8:9], 0, v[4:5]
	v_lshl_add_u64 v[6:7], v[6:7], 0, v[0:1]
	s_mov_b64 s[8:9], 0x11974000
	v_lshl_add_u64 v[26:27], v[6:7], 0, s[8:9]
	v_or_b32_e32 v4, v4, v0
	s_mov_b64 s[8:9], 0x13444000
	s_movk_i32 s14, 0x1e00
	v_or_b32_e32 v2, 0x400, v12
	v_lshlrev_b64 v[22:23], 7, v[10:11]
	v_lshlrev_b32_e32 v3, 1, v12
	v_lshl_add_u64 v[28:29], v[4:5], 0, s[8:9]
	v_mad_i64_i32 v[30:31], s[8:9], v10, s14, 0
	v_mad_i64_i32 v[32:33], s[8:9], v10, s14, v[0:1]
	v_cmp_gt_u32_e64 s[38:39], 48, v12
	v_cmp_gt_u32_e64 s[40:41], 32, v12
	v_or_b32_e32 v22, v22, v3
	v_or_b32_e32 v30, v30, v3
	s_mov_b64 s[8:9], 0
	s_lshl_b64 s[12:13], s[12:13], 2
	s_lshl_b64 s[16:17], s[16:17], 2
	v_lshlrev_b32_e32 v34, 2, v2
	s_load_dwordx2 s[88:89], s[46:47], 0xb8
	s_load_dwordx2 s[94:95], s[46:47], 0xc0
	v_lshlrev_b32_e32 v156, 2, v14
	s_waitcnt lgkmcnt(0)
	s_add_u32 s88, s88, s12
	s_addc_u32 s89, s89, s13
	s_add_u32 s94, s94, s16
	s_addc_u32 s95, s95, s17
	s_mov_b64 s[96:97], exec
	s_and_b64 exec, s[96:97], s[38:39]
	global_load_dwordx4 v[148:151], v156, s[88:89]
	global_load_dwordx4 v[152:155], v156, s[88:89] offset:16
	s_and_b64 exec, s[96:97], s[40:41]
	global_load_dwordx4 v[172:175], v156, s[94:95]
	global_load_dwordx4 v[176:179], v156, s[94:95] offset:16
	s_mov_b64 exec, s[96:97]
	s_waitcnt vmcnt(0)
	s_branch .LBB0_1052

; DI void unpack8(u32x4 w, float* v) { v[0] = lo16(w.x); v[1] = hi16(w.x); v[2] = lo16(w.y); v[3] = hi16(w.y); v[4] = lo16(w.z); v[5] = hi16(w.z); v[6] = lo16(w.w); v[7] = hi16(w.w); }
; DI u32x4 pack8(const float* v) { u32x4 w; w.x = pk2(v[0], v[1]); w.y = pk2(v[2], v[3]); w.z = pk2(v[4], v[5]); w.w = pk2(v[6], v[7]); return w; }
; DI float wave_sum(float v) { for (int o = 32; o >= 1; o >>= 1) v += __shfl_xor(v, o); return v; }
; DI void mla_row(CP c, int l, int r, int lane) {
;     ...
;         float v[8]; float ss = 0.f;
;         if (lane < 48) { unpack8(*(const u32x4*)(z + 3080 + lane * 8), v);
; #pragma unroll
;             for (int j = 0; j < 8; ++j) ss += v[j] * v[j]; }
;         const float rs = rsqrtf(wave_sum(ss) * (1.f / 384.f) + 1e-6f);
;         if (lane < 48) { const float* g = c->in[I_QNG] + l * 384 + lane * 8;
; #pragma unroll
;             for (int j = 0; j < 8; ++j) v[j] = v[j] * rs * g[j];
;             *(u32x4*)((bf16_t*)(ws + WS_QN) + (size_t)r * 384 + lane * 8) = pack8(v); }
.LBB0_1054:
	s_or_b64 exec, exec, s[18:19]
	ds_bpermute_b32 v11, v13, v0
	s_waitcnt lgkmcnt(0)
	v_add_f32_e32 v0, v0, v11
	ds_bpermute_b32 v11, v42, v0
	s_waitcnt lgkmcnt(0)
	v_add_f32_e32 v0, v0, v11
	ds_bpermute_b32 v11, v43, v0
	s_waitcnt lgkmcnt(0)
	v_add_f32_e32 v0, v0, v11
	ds_bpermute_b32 v11, v44, v0
	s_waitcnt lgkmcnt(0)
	v_add_f32_e32 v0, v0, v11
	ds_bpermute_b32 v11, v45, v0
	s_waitcnt lgkmcnt(0)
	v_add_f32_e32 v0, v0, v11
	ds_bpermute_b32 v11, v46, v0
	s_and_saveexec_b64 s[18:19], s[38:39]
	s_cbranch_execz .LBB0_1056
	v_lshlrev_b32_e32 v15, 2, v14
	s_waitcnt lgkmcnt(0)
	v_add_f32_e32 v0, v0, v11
	v_fmamk_f32 v0, v0, 0x3b2aaaab, v191
	s_mov_b32 s14, 0x800000
	v_mul_f32_e32 v11, 0x4b800000, v0
	v_cmp_gt_f32_e32 vcc, s14, v0
	s_nop 1
	v_cndmask_b32_e32 v0, v0, v11, vcc
	v_rsq_f32_e32 v0, v0
	s_nop 0
	v_mul_f32_e32 v11, 0x45800000, v0
	v_cndmask_b32_e32 v0, v0, v11, vcc
	v_pk_mul_f32 v[2:3], v[2:3], v[0:1] op_sel_hi:[1,0]
	v_pk_mul_f32 v[6:7], v[6:7], v[0:1] op_sel_hi:[1,0]
	v_pk_mul_f32 v[4:5], v[4:5], v[0:1] op_sel_hi:[1,0]
	v_pk_mul_f32 v[8:9], v[8:9], v[0:1] op_sel_hi:[1,0]
	v_pk_mul_f32 v[2:3], v[2:3], v[148:149]
	v_pk_mul_f32 v[6:7], v[6:7], v[150:151]
	v_pk_mul_f32 v[4:5], v[4:5], v[152:153]
	v_pk_mul_f32 v[8:9], v[8:9], v[154:155]
	v_cvt_pk_bf16_f32 v2, v2, v3
	v_cvt_pk_bf16_f32 v3, v6, v7
	v_cvt_pk_bf16_f32 v4, v4, v5
	v_cvt_pk_bf16_f32 v5, v8, v9
	v_lshl_add_u64 v[6:7], s[20:21], 0, v[18:19]
	global_store_dwordx4 v[6:7], v[2:5], off

; DI void unpack8(u32x4 w, float* v) { v[0] = lo16(w.x); v[1] = hi16(w.x); v[2] = lo16(w.y); v[3] = hi16(w.y); v[4] = lo16(w.z); v[5] = hi16(w.z); v[6] = lo16(w.w); v[7] = hi16(w.w); }
; DI u32x4 pack8(const float* v) { u32x4 w; w.x = pk2(v[0], v[1]); w.y = pk2(v[2], v[3]); w.z = pk2(v[4], v[5]); w.w = pk2(v[6], v[7]); return w; }
; DI float wave_sum(float v) { for (int o = 32; o >= 1; o >>= 1) v += __shfl_xor(v, o); return v; }
; DI void mla_row(CP c, int l, int r, int lane) {
;     ...
;         float v[8]; float ss = 0.f;
;         if (lane < 32) { unpack8(*(const u32x4*)(z + 3464 + lane * 8), v);
; #pragma unroll
;             for (int j = 0; j < 8; ++j) ss += v[j] * v[j]; }
;         const float rs = rsqrtf(wave_sum(ss) * (1.f / 256.f) + 1e-6f);
;         if (lane < 32) { const float* g = c->in[I_KVNG] + l * 256 + lane * 8;
; #pragma unroll
;             for (int j = 0; j < 8; ++j) v[j] = v[j] * rs * g[j];
;             *(u32x4*)((bf16_t*)(ws + WS_LAT) + (size_t)r * 256 + lane * 8) = pack8(v);
;             float* o = samp ? c->out + O_SLAT + ((size_t)(l * 32 + b) * 16 + t) * 256 + lane * 8 : c->out + O_PLAT + ((size_t)l * MP + r) * 256 + lane * 8;
;             *(f32x4*)o = (f32x4){v[0], v[1], v[2], v[3]}; *(f32x4*)(o + 4) = (f32x4){v[4], v[5], v[6], v[7]};
.LBB0_1058:
	s_or_b64 exec, exec, s[18:19]
	s_waitcnt lgkmcnt(0)
	ds_bpermute_b32 v11, v13, v0
	s_movk_i32 s14, 0x4000
	v_cmp_lt_i32_e64 s[42:43], s3, v10
	v_cmp_gt_i32_e64 s[44:45], s14, v10
	s_waitcnt lgkmcnt(0)
	v_add_f32_e32 v0, v0, v11
	ds_bpermute_b32 v11, v42, v0
	s_waitcnt lgkmcnt(0)
	v_add_f32_e32 v0, v0, v11
	ds_bpermute_b32 v11, v43, v0
	s_waitcnt lgkmcnt(0)
	v_add_f32_e32 v0, v0, v11
	ds_bpermute_b32 v11, v44, v0
	s_waitcnt lgkmcnt(0)
	v_add_f32_e32 v0, v0, v11
	ds_bpermute_b32 v11, v45, v0
	s_waitcnt lgkmcnt(0)
	v_add_f32_e32 v15, v0, v11
	ds_bpermute_b32 v35, v46, v15
	v_add_u32_e32 v0, 0xffffc000, v10
	v_ashrrev_i32_e32 v36, 4, v0
	v_and_b32_e32 v11, 15, v10
	s_and_saveexec_b64 s[18:19], s[40:41]
	s_cbranch_execz .LBB0_1070
	v_lshlrev_b32_e32 v0, 2, v14
	s_waitcnt lgkmcnt(0)
	v_add_f32_e32 v15, v15, v35
	v_fmamk_f32 v15, v15, 0x3b800000, v191
	s_mov_b32 s14, 0x800000
	v_mul_f32_e32 v35, 0x4b800000, v15
	v_cmp_gt_f32_e32 vcc, s14, v15
	s_nop 1
	v_cndmask_b32_e32 v15, v15, v35, vcc
	v_rsq_f32_e32 v15, v15
	s_nop 0
	v_mul_f32_e32 v35, 0x45800000, v15
	v_cndmask_b32_e32 v40, v15, v35, vcc
	v_pk_mul_f32 v[2:3], v[2:3], v[40:41] op_sel_hi:[1,0]
	v_pk_mul_f32 v[56:57], v[6:7], v[40:41] op_sel_hi:[1,0]
	v_pk_mul_f32 v[4:5], v[4:5], v[40:41] op_sel_hi:[1,0]
	v_pk_mul_f32 v[40:41], v[8:9], v[40:41] op_sel_hi:[1,0]
	v_pk_mul_f32 v[6:7], v[2:3], v[172:173]
	v_pk_mul_f32 v[8:9], v[56:57], v[174:175]
	v_pk_mul_f32 v[2:3], v[4:5], v[176:177]
	v_pk_mul_f32 v[4:5], v[40:41], v[178:179]
	v_cvt_pk_bf16_f32 v48, v6, v7
	v_cvt_pk_bf16_f32 v49, v8, v9
	v_cvt_pk_bf16_f32 v50, v2, v3
	v_cvt_pk_bf16_f32 v51, v4, v5
	v_lshl_add_u64 v[40:41], s[20:21], 0, v[26:27]
	global_store_dwordx4 v[40:41], v[48:51], off
	s_load_dwordx2 s[22:23], s[46:47], 0x128
	s_and_saveexec_b64 s[24:25], s[44:45]
	s_xor_b64 s[24:25], exec, s[24:25]
	s_cbranch_execz .LBB0_1061
	s_waitcnt lgkmcnt(0)
	v_lshl_add_u64 v[40:41], s[22:23], 0, v[24:25]
